# attention: + V staging lane remap (conflict-free LDS writes), block-B row-max chain overlapped with block-A exchange
# speedup vs baseline: 1.0013x; 1.0013x over previous
; __device__ __forceinline__ int otid() { int t = threadIdx.x; asm volatile("" : "+v"(t)); return t; }
; #define STOREKV(buf) do { *(u32x4*)(Kt + (buf) * KT_BYTES + kr0 * KROW + kc0 * 16) = xk0; \
;         if (tid < 256) { *(u32x4*)(Kt + (buf) * KT_BYTES + kr1 * KROW + kc1 * 16) = xa; } \
;         else { tstore_pair(Vt + (buf) * VT_BYTES, VROW, pos64(2 * va), vc8, xa, xb); } } while (0)
; __device__ __forceinline__ void attn_unit2(const bf16_t* Qm, const bf16_t* KVm, const bf16_t* P1, bf16_t* OP, int q0, int h, int klat, int nlat, int kctx, int nt, uchar* lds, bool nostore = false) {
;     const int tid = otid(), lane = tid & 63, wave = tid >> 6, l32 = lane & 31, hi = lane >> 5;
;     uchar* Kt = lds; uchar* Vt = lds + 2 * KT_BYTES;
;     const bf16_t* qrowA = Qm + (size_t)(q0 + wave * 64 + l32) * QMW + h * 96; const bf16_t* qrowB = qrowA + (size_t)32 * QMW;
;     bf16_t* orowA = OP + (size_t)(q0 + wave * 64 + l32) * P1W + 2048 + h * 64; bf16_t* orowB = orowA + (size_t)32 * P1W;
;     bf16x8 qa[6], qb[6];
; #pragma unroll
;     for (int s = 0; s < 6; ++s) { qa[s] = *(const bf16x8*)(qrowA + 16 * s + 8 * hi); qb[s] = *(const bf16x8*)(qrowB + 16 * s + 8 * hi); }
;     const int kr0 = tid / 12, kc0 = tid % 12, kr1 = (512 + tid) / 12, kc1 = (512 + tid) % 12;
;     const int tv = tid - 256, va = tv >> 3, vc8 = tv & 7;
;     u32x4 xk0, xa = (u32x4){0u, 0u, 0u, 0u}, xb = xa;
;     ...
;     LOADKV(0); STOREKV(0);
.LBB0_1084:
	s_ashr_i32 s6, s8, 4
	s_and_b32 s4, s6, -16
	v_readlane_b32 s5, v252, 50
	s_add_i32 s7, s5, s4
	v_readlane_b32 s4, v252, 60
	v_readlane_b32 s5, v252, 61
	s_and_b64 s[4:5], s[4:5], exec
	v_readlane_b32 s4, v252, 51
	s_cselect_b32 s4, s4, s8
	s_cselect_b32 s5, s7, s6
	s_ashr_i32 s9, s5, 3
	s_lshl_b32 s4, s4, 9
	s_lshl_b32 s22, s9, 13
	s_and_b32 s4, s4, 0x1e00
	v_mov_b32_e32 v10, v206
	s_or_b32 s4, s22, s4
	s_waitcnt lgkmcnt(0)
	v_and_b32_e32 v0, 0xffffffdf, v10
	s_and_b32 s6, s5, 7
	v_add_u32_e32 v220, s4, v0
	v_mov_b64_e32 v[2:3], s[0:1]
	s_movk_i32 s4, 0x600
	v_bfe_u32 v219, v10, 5, 1
	v_mad_i64_i32 v[2:3], s[4:5], v220, s4, v[2:3]
	s_mul_i32 s74, s6, 0xc0
	v_lshl_add_u64 v[2:3], v[2:3], 0, s[74:75]
	v_lshlrev_b32_e32 v0, 4, v219
	v_lshl_add_u64 v[2:3], v[2:3], 0, v[0:1]
	s_mov_b64 s[4:5], 0xc000
	v_lshl_add_u64 v[4:5], v[2:3], 0, s[4:5]
	s_mov_b32 s4, 0xc000
	v_add_co_u32_e32 v6, vcc, s4, v2
	s_mov_b32 s4, 0x2aaaaaab
	s_nop 0
	v_addc_co_u32_e32 v7, vcc, 0, v3, vcc
	global_load_dwordx4 v[130:133], v[2:3], off
	global_load_dwordx4 v[134:137], v[2:3], off offset:32
	global_load_dwordx4 v[138:141], v[4:5], off offset:32
	global_load_dwordx4 v[142:145], v[4:5], off offset:64
	global_load_dwordx4 v[146:149], v[2:3], off offset:64
	global_load_dwordx4 v[150:153], v[2:3], off offset:96
	global_load_dwordx4 v[154:157], v[4:5], off offset:96
	global_load_dwordx4 v[158:161], v[4:5], off offset:128
	global_load_dwordx4 v[162:165], v[2:3], off offset:128
	global_load_dwordx4 v[166:169], v[2:3], off offset:160
	global_load_dwordx4 v[170:173], v[6:7], off
	global_load_dwordx4 v[174:177], v[4:5], off offset:160
	v_mul_hi_i32 v2, v10, s4
	v_lshrrev_b32_e32 v3, 31, v2
	v_ashrrev_i32_e32 v2, 1, v2
	v_add_u32_e32 v221, v2, v3
	v_mul_lo_u32 v2, v221, 12
	v_sub_u32_e32 v2, v10, v2
	v_add_u32_e32 v6, s22, v221
	v_cmp_lt_i32_e64 s[38:39], 7, v2
	v_ashrrev_i32_e32 v7, 31, v6
	v_lshlrev_b32_e32 v194, 4, v2
	s_and_saveexec_b64 s[4:5], s[38:39]
	s_xor_b64 s[4:5], exec, s[4:5]
	v_mov_b64_e32 v[4:5], s[30:31]
	v_mad_i64_i32 v[4:5], s[18:19], v6, s16, v[4:5]
	v_mov_b32_e32 v195, v1
	v_lshl_add_u64 v[4:5], v[4:5], 0, v[194:195]
	v_lshl_add_u64 v[4:5], v[4:5], 0, s[82:83]
	s_or_saveexec_b64 s[4:5], s[4:5]
	v_lshlrev_b32_e32 v2, 3, v2
	s_lshl_b32 s13, s6, 6
	v_ashrrev_i32_e32 v11, 31, v2
	s_xor_b64 exec, exec, s[4:5]
	v_lshlrev_b64 v[4:5], 11, v[6:7]
	v_lshl_add_u64 v[4:5], s[92:93], 0, v[4:5]
	s_lshl_b32 s74, s13, 1
	v_lshl_add_u64 v[4:5], v[4:5], 0, s[74:75]
	v_mov_b32_e32 v3, v11
	v_lshl_add_u64 v[4:5], v[2:3], 1, v[4:5]
	s_or_b64 exec, exec, s[4:5]
	global_load_dwordx4 v[178:181], v[4:5], off
	v_and_b32_e32 v12, 31, v10
	v_bfe_u32 v3, v10, 5, 3
	s_movk_i32 s4, 0xff
	v_cmp_lt_i32_e64 s[40:41], s4, v10
	v_lshlrev_b32_e32 v4, 4, v3
	s_and_saveexec_b64 s[4:5], s[40:41]
	s_xor_b64 s[4:5], exec, s[4:5]
	s_cbranch_execz .LBB0_1090
	v_lshl_add_u32 v8, v12, 1, s22
	v_ashrrev_i32_e32 v9, 31, v8
	v_lshlrev_b64 v[6:7], 11, v[8:9]
	v_or_b32_e32 v8, 1, v8
	v_ashrrev_i32_e32 v9, 31, v8
	v_lshlrev_b64 v[8:9], 11, v[8:9]
	s_lshl_b32 s74, s13, 1
	v_lshl_add_u64 v[8:9], s[92:93], 0, v[8:9]
	v_mov_b32_e32 v5, v1
	v_lshl_add_u64 v[8:9], v[8:9], 0, s[74:75]
	v_lshl_add_u64 v[8:9], v[8:9], 0, v[4:5]
	global_load_dwordx4 v[182:185], v[8:9], off offset:1024
	v_lshl_add_u64 v[6:7], s[92:93], 0, v[6:7]
	v_lshl_add_u64 v[6:7], v[6:7], 0, s[74:75]
	v_lshl_add_u64 v[6:7], v[6:7], 0, v[4:5]
	s_mov_b64 s[6:7], 0x400
	v_lshl_add_u64 v[6:7], v[6:7], 0, s[6:7]

; #define STOREKV(buf) do { *(u32x4*)(Kt + (buf) * KT_BYTES + kr0 * KROW + kc0 * 16) = xk0; \
;         if (tid < 256) { *(u32x4*)(Kt + (buf) * KT_BYTES + kr1 * KROW + kc1 * 16) = xa; } \
;         else { tstore_pair(Vt + (buf) * VT_BYTES, VROW, pos64(2 * va), vc8, xa, xb); } } while (0)
; __device__ __forceinline__ void attn_unit2(const bf16_t* Qm, const bf16_t* KVm, const bf16_t* P1, bf16_t* OP, int q0, int h, int klat, int nlat, int kctx, int nt, uchar* lds, bool nostore = false) {
;     ...
;     const int kr0 = tid / 12, kc0 = tid % 12, kr1 = (512 + tid) / 12, kc1 = (512 + tid) % 12;
;     const int tv = tid - 256, va = tv >> 3, vc8 = tv & 7;
;     u32x4 xk0, xa = (u32x4){0u, 0u, 0u, 0u}, xb = xa;
;     ...
;     LOADKV(0); STOREKV(0);
;     __syncthreads();
;     float mA = -1e30f, mB = -1e30f, lA = 0.f, lB = 0.f; f32x16 oA0 = {}, oA1 = {}, oB0 = {}, oB1 = {};
.LBB0_1098:
	s_andn2_saveexec_b64 s[4:5], s[4:5]
	v_add3_u32 v3, 0, v224, v225
	ds_write_b128 v3, v[186:189]
	v_and_b32_e32 v3, 0x7ffffff2, v223
	v_or3_b32 v3, v9, v3, v8
	v_lshlrev_b32_e32 v7, 1, v3
	s_or_b64 exec, exec, s[4:5]
	v_and_b32_e32 v3, 31, v10
	v_mul_u32_u24_e32 v8, 0xd0, v3
	v_add3_u32 v226, 0, v8, v0
	v_and_b32_e32 v8, 64, v210
	v_xor_b32_e32 v0, 32, v210
	v_add_u32_e32 v8, 64, v8
	v_cmp_lt_i32_e32 vcc, v0, v8
	s_lshl_b32 s6, s9, 8
	s_lshl_b32 s74, s13, 1
	v_cndmask_b32_e32 v0, v210, v0, vcc
	s_add_u32 s4, s92, s74
	v_lshlrev_b32_e32 v227, 2, v0
	v_lshlrev_b32_e32 v0, 6, v3
	v_mov_b32_e32 v3, v1
	s_addc_u32 s5, s93, 0
	v_sub_u32_e32 v228, v226, v0
	v_lshl_add_u64 v[196:197], v[2:3], 1, s[30:31]
	v_mov_b32_e32 v3, v11
	v_lshlrev_b32_e32 v0, 3, v5
	v_lshl_add_u64 v[198:199], v[2:3], 1, s[4:5]
	v_cmp_lt_i32_e64 s[42:43], 7, v5
	v_ashrrev_i32_e32 v3, 31, v0
	v_mov_b32_e32 v2, v0
	v_mov_b32_e32 v5, v1
	v_mov_b32_e32 v14, v1
	v_mov_b32_e32 v15, v1
	v_lshl_add_u64 v[200:201], v[0:1], 1, s[30:31]
	v_lshl_add_u64 v[202:203], v[2:3], 1, s[4:5]
	v_add3_u32 v230, 0, v6, v7
	v_lshl_add_u64 v[204:205], s[4:5], 0, v[4:5]
	v_mov_b32_e32 v0, v1
	v_mov_b32_e32 v2, v1
	v_mov_b32_e32 v3, v1
	v_mov_b32_e32 v4, v1
	v_mov_b32_e32 v6, v1
	v_mov_b32_e32 v7, v1
	v_mov_b32_e32 v8, v1
	v_mov_b32_e32 v9, v1
	v_mov_b32_e32 v10, v1
	v_mov_b32_e32 v11, v1
	v_mov_b32_e32 v12, v1
	v_mov_b32_e32 v13, v1
	s_waitcnt lgkmcnt(1)
	v_mov_b64_e32 v[64:65], v[14:15]
	v_mov_b64_e32 v[48:49], v[14:15]
	v_mov_b64_e32 v[32:33], v[14:15]
	v_mov_b64_e32 v[62:63], v[12:13]
	v_mov_b64_e32 v[60:61], v[10:11]
	v_mov_b64_e32 v[58:59], v[8:9]
	v_mov_b64_e32 v[56:57], v[6:7]
	v_mov_b64_e32 v[54:55], v[4:5]
	v_mov_b64_e32 v[52:53], v[2:3]
	v_mov_b64_e32 v[50:51], v[0:1]
	v_mov_b64_e32 v[46:47], v[12:13]
	v_mov_b64_e32 v[44:45], v[10:11]
	v_mov_b64_e32 v[42:43], v[8:9]
	v_mov_b64_e32 v[40:41], v[6:7]
	v_mov_b64_e32 v[38:39], v[4:5]
	v_mov_b64_e32 v[36:37], v[2:3]
	v_mov_b64_e32 v[34:35], v[0:1]
	v_mov_b64_e32 v[30:31], v[12:13]
	v_mov_b64_e32 v[28:29], v[10:11]
	v_mov_b64_e32 v[26:27], v[8:9]
	v_mov_b64_e32 v[24:25], v[6:7]
	v_mov_b64_e32 v[22:23], v[4:5]
	v_mov_b64_e32 v[20:21], v[2:3]
	v_mov_b64_e32 v[18:19], v[0:1]
	v_mov_b64_e32 v[16:17], v[14:15]
	s_mov_b32 s9, 0
	s_add_i32 s13, s6, 0x6040
	s_add_i32 s22, s22, 64
	v_mov_b32_e32 v231, 0
	v_mov_b32_e32 v232, 0
	v_mov_b32_e32 v233, 0
	v_mov_b32_e32 v229, 0
	v_mov_b64_e32 v[14:15], v[12:13]
	v_mov_b64_e32 v[12:13], v[10:11]
	v_mov_b64_e32 v[10:11], v[8:9]
	v_mov_b64_e32 v[8:9], v[6:7]
	v_mov_b64_e32 v[6:7], v[4:5]
	v_mov_b64_e32 v[4:5], v[2:3]
	v_mov_b64_e32 v[2:3], v[0:1]
	v_mov_b32_e32 v197, 0x800
	v_mov_b32_e32 v196, s16
	v_cndmask_b32_e64 v196, v197, v196, s[38:39]
	v_mad_u32_u24 v196, v221, v196, v194
	v_mov_b32_e32 v198, s16
	v_cndmask_b32_e64 v198, v197, v198, s[42:43]
	v_mad_u32_u24 v198, v195, v198, v225
	v_bfe_u32 v199, v206, 5, 3
	v_lshlrev_b32_e32 v199, 4, v199
	v_lshl_add_u32 v199, v223, 11, v199
	v_add_u32_e32 v199, 0x400, v199
	v_cndmask_b32_e64 v197, v198, v199, s[40:41]
	v_and_b32_e32 v216, 63, v206
	v_mul_u32_u24_e32 v216, 0xd0, v216
	v_bfe_u32 v217, v206, 6, 1
	v_mul_u32_u24_e32 v217, 0x3400, v217
	v_add_u32_e32 v216, v216, v217
	v_mov_b32_e32 v190, 0x3f80
	v_mov_b32_e32 v191, 0
	v_mov_b32_e32 v192, 0
	v_mov_b32_e32 v193, 0
	ds_write_b128 v216, v[190:193] offset:192
	s_waitcnt lgkmcnt(0)
	v_mov_b32_e32 v190, 0
	v_mov_b32_e32 v216, 0
	v_mov_b32_e32 v217, 0
	v_mov_b32_e32 v218, 0
	v_mov_b32_e32 v219, 0
	s_waitcnt lgkmcnt(0)
	s_barrier
	s_branch .LBB0_1103

; #define MFMA32(a, b, c) __builtin_amdgcn_mfma_f32_32x32x16_bf16((a), (b), (c), 0, 0, 0)
; __device__ __forceinline__ void attn_unit2(const bf16_t* Qm, const bf16_t* KVm, const bf16_t* P1, bf16_t* OP, int q0, int h, int klat, int nlat, int kctx, int nt, uchar* lds, bool nostore = false) {
;     ...
;         f32x16 sA0 = {}, sA1 = {}, sB0 = {}, sB1 = {};
;         { const uchar* kb = Kt + buf * KT_BYTES + l32 * KROW + hi * 16;
; #pragma unroll
;           for (int s = 0; s < 6; ++s) { const bf16x8 a0 = *(const bf16x8*)(kb + s * 32), a1 = *(const bf16x8*)(kb + 32 * KROW + s * 32);
;               sA0 = MFMA32(a0, qa[s], sA0); sA1 = MFMA32(a1, qa[s], sA1); sB0 = MFMA32(a0, qb[s], sB0); sB1 = MFMA32(a1, qb[s], sB1); } }
.LBB0_1117:
	s_and_b32 s4, s9, 1
	s_mul_i32 s5, s4, 0x3400
	v_add_u32_e32 v0, s5, v226
	ds_read_b128 v[246:249], v0 offset:176
	ds_read_b128 v[66:69], v0
	ds_read_b128 v[70:73], v0 offset:32
	ds_read_b128 v[74:77], v0 offset:6656
	ds_read_b128 v[234:237], v0 offset:6688
	ds_read_b128 v[208:211], v0 offset:6832
	s_waitcnt lgkmcnt(5)
	v_mfma_f32_32x32x16_bf16 v[114:129], v[246:249], v[216:219], 0
	v_mfma_f32_32x32x16_bf16 v[98:113], v[246:249], v[190:193], 0
	s_waitcnt lgkmcnt(4)
	v_mfma_f32_32x32x16_bf16 v[114:129], v[66:69], v[130:133], v[114:129]
	v_mfma_f32_32x32x16_bf16 v[98:113], v[66:69], v[170:173], v[98:113]
	s_waitcnt lgkmcnt(3)
	v_mfma_f32_32x32x16_bf16 v[114:129], v[70:73], v[134:137], v[114:129]
	v_mfma_f32_32x32x16_bf16 v[98:113], v[70:73], v[138:141], v[98:113]
	ds_read_b128 v[66:69], v0 offset:64
	ds_read_b128 v[70:73], v0 offset:96
	ds_read_b128 v[238:241], v0 offset:6720
	ds_read_b128 v[242:245], v0 offset:6752
	s_waitcnt lgkmcnt(3)
	v_mfma_f32_32x32x16_bf16 v[114:129], v[66:69], v[146:149], v[114:129]
	v_mfma_f32_32x32x16_bf16 v[98:113], v[66:69], v[142:145], v[98:113]
	v_mfma_f32_32x32x16_bf16 v[82:97], v[208:211], v[216:219], 0
	v_mfma_f32_32x32x16_bf16 v[82:97], v[74:77], v[130:133], v[82:97]
	s_waitcnt lgkmcnt(2)
	v_mfma_f32_32x32x16_bf16 v[114:129], v[70:73], v[150:153], v[114:129]
	v_mfma_f32_32x32x16_bf16 v[98:113], v[70:73], v[154:157], v[98:113]
	ds_read_b128 v[66:69], v0 offset:128
	ds_read_b128 v[70:73], v0 offset:160
	ds_read_b128 v[246:249], v0 offset:6784
	ds_read_b128 v[212:215], v0 offset:6816
	v_mfma_f32_32x32x16_bf16 v[82:97], v[234:237], v[134:137], v[82:97]
	s_waitcnt lgkmcnt(3)
	v_mfma_f32_32x32x16_bf16 v[114:129], v[66:69], v[162:165], v[114:129]
	v_mfma_f32_32x32x16_bf16 v[98:113], v[66:69], v[158:161], v[98:113]
	v_mfma_f32_32x32x16_bf16 v[82:97], v[238:241], v[146:149], v[82:97]
	s_waitcnt lgkmcnt(2)
	v_mfma_f32_32x32x16_bf16 v[114:129], v[70:73], v[166:169], v[114:129]
	v_mfma_f32_32x32x16_bf16 v[98:113], v[70:73], v[174:177], v[98:113]
	s_nop 10
	v_max_f32_e32 v0, v115, v115
	v_mfma_f32_32x32x16_bf16 v[66:81], v[74:77], v[170:173], 0
	v_mfma_f32_32x32x16_bf16 v[66:81], v[208:211], v[190:193], v[66:81]
	v_mfma_f32_32x32x16_bf16 v[82:97], v[242:245], v[150:153], v[82:97]
	v_mfma_f32_32x32x16_bf16 v[66:81], v[234:237], v[138:141], v[66:81]
	v_max_f32_e32 v234, v114, v114
	v_max_f32_e32 v0, v234, v0
	s_waitcnt lgkmcnt(1)
	v_mfma_f32_32x32x16_bf16 v[82:97], v[246:249], v[162:165], v[82:97]
	v_mfma_f32_32x32x16_bf16 v[66:81], v[238:241], v[142:145], v[66:81]
	s_waitcnt lgkmcnt(0)
	v_mfma_f32_32x32x16_bf16 v[82:97], v[212:215], v[166:169], v[82:97]
	v_mfma_f32_32x32x16_bf16 v[66:81], v[242:245], v[154:157], v[66:81]
	s_nop 10
	v_max3_f32 v234, v116, v117, v83
	v_max3_f32 v0, v0, v82, v84
	v_max3_f32 v0, v0, v85, v118
	v_max3_f32 v234, v234, v120, v121
	v_max3_f32 v0, v0, v119, v86
	v_max3_f32 v234, v234, v88, v89
	v_max3_f32 v0, v0, v87, v122
	v_mfma_f32_32x32x16_bf16 v[66:81], v[246:249], v[158:161], v[66:81]
	v_max3_f32 v234, v234, v124, v125
	v_max3_f32 v0, v0, v123, v90
	v_max3_f32 v234, v234, v92, v93
	v_max3_f32 v0, v0, v91, v126
	v_max3_f32 v234, v234, v128, v129
	v_max3_f32 v0, v0, v127, v94
	v_max3_f32 v234, v234, v96, v97
	v_max3_f32 v0, v0, v95, v234
	ds_bpermute_b32 v234, v227, v0
	v_mfma_f32_32x32x16_bf16 v[66:81], v[212:215], v[174:177], v[66:81]
	v_max3_f32 v235, v98, v99, v100
	v_max3_f32 v236, v101, v102, v103
	v_max3_f32 v235, v235, v104, v105
	v_max3_f32 v236, v236, v106, v107
	v_max3_f32 v235, v235, v108, v109
	v_max3_f32 v236, v236, v110, v111
	v_max3_f32 v235, v235, v112, v113
	s_nop 4
	v_max3_f32 v236, v236, v66, v67
	v_max3_f32 v235, v235, v68, v69
	v_max3_f32 v236, v236, v70, v71
	v_max3_f32 v235, v235, v72, v73
	v_max3_f32 v236, v236, v74, v75
	v_max3_f32 v235, v235, v76, v77
	v_max3_f32 v236, v236, v78, v79
	v_max3_f32 v235, v235, v80, v81
	v_max_f32_e32 v235, v235, v236
	ds_bpermute_b32 v236, v227, v235
	s_waitcnt lgkmcnt(1)
	v_max_f32_e32 v234, v234, v234
	v_max_f32_e32 v0, v0, v234
	v_cmp_lt_f32_e32 vcc, 0x41000000, v0
	s_cmp_eq_u32 s9, 0
	s_cbranch_scc1 .Latt_rareA
	s_cbranch_vccz .LBB0_1119

.LBB0_1119:
	s_waitcnt lgkmcnt(0)
	v_max_f32_e32 v236, v236, v236
	v_max_f32_e32 v0, v235, v236
	v_cmp_lt_f32_e32 vcc, 0x41000000, v0
	s_cmp_eq_u32 s9, 0
	s_cbranch_scc1 .Latt_rareB
	s_cbranch_vccz .LBB0_1121
